# v41 with MFMA order: accumulate distance 2 (pairs sharing the A fragment, then their k=1 partners)
# baseline (speedup 1.0000x reference)
.LBB0_159:
	s_add_u32 s0, s22, 0xfff80080
	s_addc_u32 s1, s23, -1
	s_add_i32 s51, 0, 0x10000
	s_cmp_eq_u32 s50, 28
	s_cselect_b32 s27, s15, s1
	s_cselect_b32 s26, s46, s0
	v_add_u32_e32 v140, s51, v143
	s_cselect_b32 s25, s13, s49
	s_cselect_b32 s24, s47, s48
	s_add_i32 s0, 0, 0x14000
	ds_read_b128 v[146:149], v140
	ds_read_b128 v[150:153], v140 offset:1024
	ds_read_b128 v[154:157], v140 offset:2048
	ds_read_b128 v[158:161], v140 offset:3072
	v_add_u32_e32 v140, s0, v143
	ds_read_b128 v[162:165], v140
	ds_read_b128 v[166:169], v140 offset:1024
	ds_read_b128 v[170:173], v140 offset:2048
	ds_read_b128 v[174:177], v140 offset:3072
	v_lshl_add_u64 v[140:141], s[22:23], 0, v[136:137]
	s_add_i32 m0, s35, 0xc000
	ds_read_b128 v[178:181], v144
	ds_read_b128 v[182:185], v144 offset:1024
	ds_read_b128 v[192:195], v144 offset:2048
	ds_read_b128 v[196:199], v144 offset:3072
	ds_read_b128 v[200:203], v144 offset:4096
	ds_read_b128 v[204:207], v144 offset:5120
	ds_read_b128 v[208:211], v144 offset:6144
	ds_read_b128 v[212:215], v144 offset:7168
	global_load_lds_dwordx4 v[140:141], off
	v_lshl_add_u64 v[140:141], s[22:23], 0, v[138:139]
	s_add_i32 m0, s35, 0xe000
	s_nop 0
	global_load_lds_dwordx4 v[140:141], off
	s_waitcnt vmcnt(8)
	s_waitcnt lgkmcnt(0)
	s_setprio 1
	s_barrier

	v_mfma_f32_16x16x32_bf16 v[126:129], v[146:149], v[178:181], v[126:129]
	v_mfma_f32_16x16x32_bf16 v[118:121], v[154:157], v[178:181], v[118:121]
	v_mfma_f32_16x16x32_bf16 v[126:129], v[150:153], v[182:185], v[126:129]
	v_mfma_f32_16x16x32_bf16 v[118:121], v[158:161], v[182:185], v[118:121]
	v_mfma_f32_16x16x32_bf16 v[110:113], v[146:149], v[192:195], v[110:113]
	v_mfma_f32_16x16x32_bf16 v[102:105], v[154:157], v[192:195], v[102:105]
	v_mfma_f32_16x16x32_bf16 v[110:113], v[150:153], v[196:199], v[110:113]
	v_mfma_f32_16x16x32_bf16 v[102:105], v[158:161], v[196:199], v[102:105]
	v_mfma_f32_16x16x32_bf16 v[94:97], v[146:149], v[200:203], v[94:97]
	v_mfma_f32_16x16x32_bf16 v[86:89], v[154:157], v[200:203], v[86:89]
	v_mfma_f32_16x16x32_bf16 v[94:97], v[150:153], v[204:207], v[94:97]
	v_mfma_f32_16x16x32_bf16 v[86:89], v[158:161], v[204:207], v[86:89]
	v_mfma_f32_16x16x32_bf16 v[78:81], v[146:149], v[208:211], v[78:81]
	v_mfma_f32_16x16x32_bf16 v[70:73], v[154:157], v[208:211], v[70:73]
	v_mfma_f32_16x16x32_bf16 v[78:81], v[150:153], v[212:215], v[78:81]
	v_mfma_f32_16x16x32_bf16 v[70:73], v[158:161], v[212:215], v[70:73]


	v_mfma_f32_16x16x32_bf16 v[122:125], v[162:165], v[178:181], v[122:125]
	v_mfma_f32_16x16x32_bf16 v[114:117], v[170:173], v[178:181], v[114:117]
	v_mfma_f32_16x16x32_bf16 v[122:125], v[166:169], v[182:185], v[122:125]
	v_mfma_f32_16x16x32_bf16 v[114:117], v[174:177], v[182:185], v[114:117]
	v_mfma_f32_16x16x32_bf16 v[106:109], v[162:165], v[192:195], v[106:109]
	v_mfma_f32_16x16x32_bf16 v[98:101], v[170:173], v[192:195], v[98:101]
	v_mfma_f32_16x16x32_bf16 v[106:109], v[166:169], v[196:199], v[106:109]
	v_mfma_f32_16x16x32_bf16 v[98:101], v[174:177], v[196:199], v[98:101]
	v_mfma_f32_16x16x32_bf16 v[90:93], v[162:165], v[200:203], v[90:93]
	v_mfma_f32_16x16x32_bf16 v[82:85], v[170:173], v[200:203], v[82:85]
	v_mfma_f32_16x16x32_bf16 v[90:93], v[166:169], v[204:207], v[90:93]
	v_mfma_f32_16x16x32_bf16 v[82:85], v[174:177], v[204:207], v[82:85]
	v_mfma_f32_16x16x32_bf16 v[74:77], v[162:165], v[208:211], v[74:77]
	v_mfma_f32_16x16x32_bf16 v[66:69], v[170:173], v[208:211], v[66:69]
	v_mfma_f32_16x16x32_bf16 v[74:77], v[166:169], v[212:215], v[74:77]
	v_mfma_f32_16x16x32_bf16 v[66:69], v[174:177], v[212:215], v[66:69]
	s_barrier
	s_setprio 0
	s_add_i32 s1, s51, s31
	v_lshl_add_u64 v[140:141], s[24:25], 0, v[186:187]
	s_mov_b32 m0, s1
	ds_read_b128 v[178:181], v144 offset:16384
	ds_read_b128 v[182:185], v144 offset:17408
	ds_read_b128 v[192:195], v144 offset:18432
	ds_read_b128 v[196:199], v144 offset:19456
	ds_read_b128 v[200:203], v144 offset:20480
	ds_read_b128 v[204:207], v144 offset:21504
	ds_read_b128 v[208:211], v144 offset:22528
	ds_read_b128 v[212:215], v144 offset:23552
	global_load_lds_dwordx4 v[140:141], off
	s_add_i32 m0, s1, 0x2000
	s_add_u32 s52, s24, 0x80000
	v_lshl_add_u64 v[216:217], s[24:25], 0, v[130:131]
	s_addc_u32 s53, s25, 0
	s_add_i32 s0, s0, s31
	global_load_lds_dwordx4 v[216:217], off
	v_lshl_add_u64 v[218:219], s[52:53], 0, v[186:187]
	s_mov_b32 m0, s0
	v_lshl_add_u64 v[220:221], s[26:27], 0, v[132:133]
	global_load_lds_dwordx4 v[218:219], off
	v_lshl_add_u64 v[218:219], s[52:53], 0, v[130:131]
	s_add_i32 m0, s0, 0x2000
	s_nop 0
	global_load_lds_dwordx4 v[218:219], off
	v_lshl_add_u64 v[218:219], s[26:27], 0, v[134:135]
	s_mov_b32 m0, s35
	s_nop 0
	global_load_lds_dwordx4 v[218:219], off
	s_mov_b32 m0, s36
	s_nop 0
	global_load_lds_dwordx4 v[220:221], off
	s_waitcnt vmcnt(8)
	s_waitcnt lgkmcnt(0)
	s_setprio 1
	s_barrier

	v_mfma_f32_16x16x32_bf16 v[62:65], v[146:149], v[178:181], v[62:65]
	v_mfma_f32_16x16x32_bf16 v[54:57], v[154:157], v[178:181], v[54:57]
	v_mfma_f32_16x16x32_bf16 v[62:65], v[150:153], v[182:185], v[62:65]
	v_mfma_f32_16x16x32_bf16 v[54:57], v[158:161], v[182:185], v[54:57]
	v_mfma_f32_16x16x32_bf16 v[46:49], v[146:149], v[192:195], v[46:49]
	v_mfma_f32_16x16x32_bf16 v[38:41], v[154:157], v[192:195], v[38:41]
	v_mfma_f32_16x16x32_bf16 v[46:49], v[150:153], v[196:199], v[46:49]
	v_mfma_f32_16x16x32_bf16 v[38:41], v[158:161], v[196:199], v[38:41]
	v_mfma_f32_16x16x32_bf16 v[30:33], v[146:149], v[200:203], v[30:33]
	v_mfma_f32_16x16x32_bf16 v[22:25], v[154:157], v[200:203], v[22:25]
	v_mfma_f32_16x16x32_bf16 v[30:33], v[150:153], v[204:207], v[30:33]
	v_mfma_f32_16x16x32_bf16 v[22:25], v[158:161], v[204:207], v[22:25]
	v_mfma_f32_16x16x32_bf16 v[14:17], v[146:149], v[208:211], v[14:17]
	v_mfma_f32_16x16x32_bf16 v[6:9], v[154:157], v[208:211], v[6:9]
	v_mfma_f32_16x16x32_bf16 v[14:17], v[150:153], v[212:215], v[14:17]
	v_mfma_f32_16x16x32_bf16 v[6:9], v[158:161], v[212:215], v[6:9]


	v_mfma_f32_16x16x32_bf16 v[58:61], v[162:165], v[178:181], v[58:61]
	v_mfma_f32_16x16x32_bf16 v[50:53], v[170:173], v[178:181], v[50:53]
	v_mfma_f32_16x16x32_bf16 v[58:61], v[166:169], v[182:185], v[58:61]
	v_mfma_f32_16x16x32_bf16 v[50:53], v[174:177], v[182:185], v[50:53]
	v_mfma_f32_16x16x32_bf16 v[42:45], v[162:165], v[192:195], v[42:45]
	v_mfma_f32_16x16x32_bf16 v[34:37], v[170:173], v[192:195], v[34:37]
	v_mfma_f32_16x16x32_bf16 v[42:45], v[166:169], v[196:199], v[42:45]
	v_mfma_f32_16x16x32_bf16 v[34:37], v[174:177], v[196:199], v[34:37]
	v_mfma_f32_16x16x32_bf16 v[26:29], v[162:165], v[200:203], v[26:29]
	v_mfma_f32_16x16x32_bf16 v[18:21], v[170:173], v[200:203], v[18:21]
	v_mfma_f32_16x16x32_bf16 v[26:29], v[166:169], v[204:207], v[26:29]
	v_mfma_f32_16x16x32_bf16 v[18:21], v[174:177], v[204:207], v[18:21]
	v_mfma_f32_16x16x32_bf16 v[10:13], v[162:165], v[208:211], v[10:13]
	v_mfma_f32_16x16x32_bf16 v[2:5], v[170:173], v[208:211], v[2:5]
	v_mfma_f32_16x16x32_bf16 v[10:13], v[166:169], v[212:215], v[10:13]
	v_mfma_f32_16x16x32_bf16 v[2:5], v[174:177], v[212:215], v[2:5]
	s_barrier
	s_setprio 0
	s_add_i32 s0, 0, 0x18000
	v_add_u32_e32 v145, s0, v143
	s_add_i32 s1, 0, 0x1c000
	ds_read_b128 v[146:149], v145
	ds_read_b128 v[150:153], v145 offset:1024
	ds_read_b128 v[154:157], v145 offset:2048
	ds_read_b128 v[158:161], v145 offset:3072
	v_add_u32_e32 v145, s1, v143
	ds_read_b128 v[162:165], v145
	ds_read_b128 v[166:169], v145 offset:1024
	ds_read_b128 v[170:173], v145 offset:2048
	ds_read_b128 v[174:177], v145 offset:3072
	s_add_u32 s26, s26, 0x80000
	s_addc_u32 s27, s27, 0
	s_mov_b32 m0, s37
	v_lshl_add_u64 v[222:223], s[26:27], 0, v[134:135]
	ds_read_b128 v[178:181], v144 offset:32768
	ds_read_b128 v[182:185], v144 offset:33792
	ds_read_b128 v[192:195], v144 offset:34816
	ds_read_b128 v[196:199], v144 offset:35840
	ds_read_b128 v[200:203], v144 offset:36864
	ds_read_b128 v[204:207], v144 offset:37888
	ds_read_b128 v[208:211], v144 offset:38912
	ds_read_b128 v[212:215], v144 offset:39936
	global_load_lds_dwordx4 v[222:223], off
	v_lshl_add_u64 v[222:223], s[26:27], 0, v[132:133]
	s_mov_b32 m0, s38
	s_nop 0
	global_load_lds_dwordx4 v[222:223], off
	s_waitcnt vmcnt(8)
	s_waitcnt lgkmcnt(0)
	s_setprio 1
	s_barrier

	v_mfma_f32_16x16x32_bf16 v[126:129], v[146:149], v[178:181], v[126:129]
	v_mfma_f32_16x16x32_bf16 v[118:121], v[154:157], v[178:181], v[118:121]
	v_mfma_f32_16x16x32_bf16 v[126:129], v[150:153], v[182:185], v[126:129]
	v_mfma_f32_16x16x32_bf16 v[118:121], v[158:161], v[182:185], v[118:121]
	v_mfma_f32_16x16x32_bf16 v[110:113], v[146:149], v[192:195], v[110:113]
	v_mfma_f32_16x16x32_bf16 v[102:105], v[154:157], v[192:195], v[102:105]
	v_mfma_f32_16x16x32_bf16 v[110:113], v[150:153], v[196:199], v[110:113]
	v_mfma_f32_16x16x32_bf16 v[102:105], v[158:161], v[196:199], v[102:105]
	v_mfma_f32_16x16x32_bf16 v[94:97], v[146:149], v[200:203], v[94:97]
	v_mfma_f32_16x16x32_bf16 v[86:89], v[154:157], v[200:203], v[86:89]
	v_mfma_f32_16x16x32_bf16 v[94:97], v[150:153], v[204:207], v[94:97]
	v_mfma_f32_16x16x32_bf16 v[86:89], v[158:161], v[204:207], v[86:89]
	v_mfma_f32_16x16x32_bf16 v[78:81], v[146:149], v[208:211], v[78:81]
	v_mfma_f32_16x16x32_bf16 v[70:73], v[154:157], v[208:211], v[70:73]
	v_mfma_f32_16x16x32_bf16 v[78:81], v[150:153], v[212:215], v[78:81]
	v_mfma_f32_16x16x32_bf16 v[70:73], v[158:161], v[212:215], v[70:73]


	v_mfma_f32_16x16x32_bf16 v[122:125], v[162:165], v[178:181], v[122:125]
	v_mfma_f32_16x16x32_bf16 v[114:117], v[170:173], v[178:181], v[114:117]
	v_mfma_f32_16x16x32_bf16 v[122:125], v[166:169], v[182:185], v[122:125]
	v_mfma_f32_16x16x32_bf16 v[114:117], v[174:177], v[182:185], v[114:117]
	v_mfma_f32_16x16x32_bf16 v[106:109], v[162:165], v[192:195], v[106:109]
	v_mfma_f32_16x16x32_bf16 v[98:101], v[170:173], v[192:195], v[98:101]
	v_mfma_f32_16x16x32_bf16 v[106:109], v[166:169], v[196:199], v[106:109]
	v_mfma_f32_16x16x32_bf16 v[98:101], v[174:177], v[196:199], v[98:101]
	v_mfma_f32_16x16x32_bf16 v[90:93], v[162:165], v[200:203], v[90:93]
	v_mfma_f32_16x16x32_bf16 v[82:85], v[170:173], v[200:203], v[82:85]
	v_mfma_f32_16x16x32_bf16 v[90:93], v[166:169], v[204:207], v[90:93]
	v_mfma_f32_16x16x32_bf16 v[82:85], v[174:177], v[204:207], v[82:85]
	v_mfma_f32_16x16x32_bf16 v[74:77], v[162:165], v[208:211], v[74:77]
	v_mfma_f32_16x16x32_bf16 v[66:69], v[170:173], v[208:211], v[66:69]
	v_mfma_f32_16x16x32_bf16 v[74:77], v[166:169], v[212:215], v[74:77]
	v_mfma_f32_16x16x32_bf16 v[66:69], v[174:177], v[212:215], v[66:69]
	s_barrier
	s_setprio 0
	s_add_i32 s0, s0, s31
	v_lshl_add_u64 v[140:141], v[140:141], 0, s[84:85]
	s_mov_b32 m0, s0
	ds_read_b128 v[178:181], v144 offset:49152
	ds_read_b128 v[182:185], v144 offset:50176
	ds_read_b128 v[192:195], v144 offset:51200
	ds_read_b128 v[196:199], v144 offset:52224
	ds_read_b128 v[200:203], v144 offset:53248
	ds_read_b128 v[204:207], v144 offset:54272
	ds_read_b128 v[208:211], v144 offset:55296
	ds_read_b128 v[212:215], v144 offset:56320
	global_load_lds_dwordx4 v[140:141], off
	s_add_i32 m0, s0, 0x2000
	s_add_u32 s24, s24, 0x80080
	v_lshl_add_u64 v[140:141], v[216:217], 0, s[84:85]
	s_addc_u32 s25, s25, 0
	s_add_i32 s0, s1, s31
	global_load_lds_dwordx4 v[140:141], off
	v_lshl_add_u64 v[140:141], s[24:25], 0, v[186:187]
	s_mov_b32 m0, s0
	s_nop 0
	global_load_lds_dwordx4 v[140:141], off
	v_lshl_add_u64 v[140:141], s[24:25], 0, v[130:131]
	s_add_i32 m0, s0, 0x2000
	s_nop 0
	global_load_lds_dwordx4 v[140:141], off
	v_lshl_add_u64 v[140:141], v[218:219], 0, s[84:85]
	s_mov_b32 m0, s39
	s_nop 0
	global_load_lds_dwordx4 v[140:141], off
	v_lshl_add_u64 v[140:141], v[220:221], 0, s[84:85]
	s_mov_b32 m0, s40
	s_nop 0
	global_load_lds_dwordx4 v[140:141], off
	s_waitcnt vmcnt(8)
	s_waitcnt lgkmcnt(0)
	s_setprio 1
	s_barrier

	v_mfma_f32_16x16x32_bf16 v[62:65], v[146:149], v[178:181], v[62:65]
	v_mfma_f32_16x16x32_bf16 v[54:57], v[154:157], v[178:181], v[54:57]
	v_mfma_f32_16x16x32_bf16 v[62:65], v[150:153], v[182:185], v[62:65]
	v_mfma_f32_16x16x32_bf16 v[54:57], v[158:161], v[182:185], v[54:57]
	v_mfma_f32_16x16x32_bf16 v[46:49], v[146:149], v[192:195], v[46:49]
	v_mfma_f32_16x16x32_bf16 v[38:41], v[154:157], v[192:195], v[38:41]
	v_mfma_f32_16x16x32_bf16 v[46:49], v[150:153], v[196:199], v[46:49]
	v_mfma_f32_16x16x32_bf16 v[38:41], v[158:161], v[196:199], v[38:41]
	v_mfma_f32_16x16x32_bf16 v[30:33], v[146:149], v[200:203], v[30:33]
	v_mfma_f32_16x16x32_bf16 v[22:25], v[154:157], v[200:203], v[22:25]
	v_mfma_f32_16x16x32_bf16 v[30:33], v[150:153], v[204:207], v[30:33]
	v_mfma_f32_16x16x32_bf16 v[22:25], v[158:161], v[204:207], v[22:25]
	v_mfma_f32_16x16x32_bf16 v[14:17], v[146:149], v[208:211], v[14:17]
	v_mfma_f32_16x16x32_bf16 v[6:9], v[154:157], v[208:211], v[6:9]
	v_mfma_f32_16x16x32_bf16 v[14:17], v[150:153], v[212:215], v[14:17]
	v_mfma_f32_16x16x32_bf16 v[6:9], v[158:161], v[212:215], v[6:9]


	v_mfma_f32_16x16x32_bf16 v[58:61], v[162:165], v[178:181], v[58:61]
	v_mfma_f32_16x16x32_bf16 v[50:53], v[170:173], v[178:181], v[50:53]
	v_mfma_f32_16x16x32_bf16 v[58:61], v[166:169], v[182:185], v[58:61]
	v_mfma_f32_16x16x32_bf16 v[50:53], v[174:177], v[182:185], v[50:53]
	v_mfma_f32_16x16x32_bf16 v[42:45], v[162:165], v[192:195], v[42:45]
	v_mfma_f32_16x16x32_bf16 v[34:37], v[170:173], v[192:195], v[34:37]
	v_mfma_f32_16x16x32_bf16 v[42:45], v[166:169], v[196:199], v[42:45]
	v_mfma_f32_16x16x32_bf16 v[34:37], v[174:177], v[196:199], v[34:37]
	v_mfma_f32_16x16x32_bf16 v[26:29], v[162:165], v[200:203], v[26:29]
	v_mfma_f32_16x16x32_bf16 v[18:21], v[170:173], v[200:203], v[18:21]
	v_mfma_f32_16x16x32_bf16 v[26:29], v[166:169], v[204:207], v[26:29]
	v_mfma_f32_16x16x32_bf16 v[18:21], v[174:177], v[204:207], v[18:21]
	v_mfma_f32_16x16x32_bf16 v[10:13], v[162:165], v[208:211], v[10:13]
	v_mfma_f32_16x16x32_bf16 v[2:5], v[170:173], v[208:211], v[2:5]
	v_mfma_f32_16x16x32_bf16 v[10:13], v[166:169], v[212:215], v[10:13]
	v_mfma_f32_16x16x32_bf16 v[2:5], v[174:177], v[212:215], v[2:5]
	s_barrier
	s_setprio 0
	s_add_i32 s50, s50, 2
	s_add_u32 s22, s22, 0x100
	s_addc_u32 s23, s23, 0
	s_add_u32 s48, s48, 0x100
	s_addc_u32 s49, s49, 0
	s_cmp_gt_u32 s50, 29
	s_cbranch_scc0 .LBB0_159
	s_and_b64 vcc, exec, s[10:11]
	s_cbranch_vccz .LBB0_162
	s_barrier

.LBB0_243:
	s_add_u32 s22, s20, 0x100
	s_addc_u32 s23, s21, 0
	s_add_i32 s0, 0, 0x10000
	s_cmpk_eq_i32 s51, 0x54
	s_cselect_b32 s27, s7, s23
	s_cselect_b32 s26, s6, s22
	s_cselect_b32 s25, s19, s50
	s_cselect_b32 s24, s18, s49
	s_add_i32 s1, 0, 0x14000
	v_add_u32_e32 v126, s0, v237
	v_add_u32_e32 v158, s1, v237
	ds_read_b128 v[90:93], v126
	ds_read_b128 v[102:105], v126 offset:1024
	ds_read_b128 v[114:117], v126 offset:2048
	ds_read_b128 v[126:129], v126 offset:3072
	ds_read_b128 v[138:141], v158
	ds_read_b128 v[142:145], v158 offset:1024
	ds_read_b128 v[154:157], v158 offset:2048
	ds_read_b128 v[158:161], v158 offset:3072
	v_lshl_add_u64 v[210:211], s[20:21], 0, v[198:199]
	s_add_i32 m0, s34, 0xc000
	ds_read_b128 v[162:165], v238
	ds_read_b128 v[166:169], v238 offset:1024
	ds_read_b128 v[170:173], v238 offset:2048
	ds_read_b128 v[174:177], v238 offset:3072
	ds_read_b128 v[178:181], v238 offset:4096
	ds_read_b128 v[182:185], v238 offset:5120
	ds_read_b128 v[202:205], v238 offset:6144
	ds_read_b128 v[206:209], v238 offset:7168
	global_load_lds_dwordx4 v[210:211], off
	v_lshl_add_u64 v[210:211], s[20:21], 0, v[200:201]
	s_add_i32 m0, s34, 0xe000
	s_nop 0
	global_load_lds_dwordx4 v[210:211], off
	s_waitcnt vmcnt(8)
	s_waitcnt lgkmcnt(0)
	s_setprio 1
	s_barrier

	v_mfma_f32_16x16x32_bf16 v[150:153], v[90:93], v[162:165], v[150:153]
	v_mfma_f32_16x16x32_bf16 v[146:149], v[114:117], v[162:165], v[146:149]
	v_mfma_f32_16x16x32_bf16 v[150:153], v[102:105], v[166:169], v[150:153]
	v_mfma_f32_16x16x32_bf16 v[146:149], v[126:129], v[166:169], v[146:149]
	v_mfma_f32_16x16x32_bf16 v[122:125], v[90:93], v[170:173], v[122:125]
	v_mfma_f32_16x16x32_bf16 v[118:121], v[114:117], v[170:173], v[118:121]
	v_mfma_f32_16x16x32_bf16 v[122:125], v[102:105], v[174:177], v[122:125]
	v_mfma_f32_16x16x32_bf16 v[118:121], v[126:129], v[174:177], v[118:121]
	v_mfma_f32_16x16x32_bf16 v[98:101], v[90:93], v[178:181], v[98:101]
	v_mfma_f32_16x16x32_bf16 v[94:97], v[114:117], v[178:181], v[94:97]
	v_mfma_f32_16x16x32_bf16 v[98:101], v[102:105], v[182:185], v[98:101]
	v_mfma_f32_16x16x32_bf16 v[94:97], v[126:129], v[182:185], v[94:97]
	v_mfma_f32_16x16x32_bf16 v[78:81], v[90:93], v[202:205], v[78:81]
	v_mfma_f32_16x16x32_bf16 v[74:77], v[114:117], v[202:205], v[74:77]
	v_mfma_f32_16x16x32_bf16 v[78:81], v[102:105], v[206:209], v[78:81]
	v_mfma_f32_16x16x32_bf16 v[74:77], v[126:129], v[206:209], v[74:77]


	v_mfma_f32_16x16x32_bf16 v[134:137], v[138:141], v[162:165], v[134:137]
	v_mfma_f32_16x16x32_bf16 v[130:133], v[154:157], v[162:165], v[130:133]
	v_mfma_f32_16x16x32_bf16 v[134:137], v[142:145], v[166:169], v[134:137]
	v_mfma_f32_16x16x32_bf16 v[130:133], v[158:161], v[166:169], v[130:133]
	v_mfma_f32_16x16x32_bf16 v[110:113], v[138:141], v[170:173], v[110:113]
	v_mfma_f32_16x16x32_bf16 v[106:109], v[154:157], v[170:173], v[106:109]
	v_mfma_f32_16x16x32_bf16 v[110:113], v[142:145], v[174:177], v[110:113]
	v_mfma_f32_16x16x32_bf16 v[106:109], v[158:161], v[174:177], v[106:109]
	v_mfma_f32_16x16x32_bf16 v[86:89], v[138:141], v[178:181], v[86:89]
	v_mfma_f32_16x16x32_bf16 v[82:85], v[154:157], v[178:181], v[82:85]
	v_mfma_f32_16x16x32_bf16 v[86:89], v[142:145], v[182:185], v[86:89]
	v_mfma_f32_16x16x32_bf16 v[82:85], v[158:161], v[182:185], v[82:85]
	v_mfma_f32_16x16x32_bf16 v[70:73], v[138:141], v[202:205], v[70:73]
	v_mfma_f32_16x16x32_bf16 v[66:69], v[154:157], v[202:205], v[66:69]
	v_mfma_f32_16x16x32_bf16 v[70:73], v[142:145], v[206:209], v[70:73]
	v_mfma_f32_16x16x32_bf16 v[66:69], v[158:161], v[206:209], v[66:69]
	s_barrier
	s_setprio 0
	s_add_i32 s0, s0, s31
	v_lshl_add_u64 v[210:211], s[24:25], 0, v[186:187]
	s_mov_b32 m0, s0
	ds_read_b128 v[162:165], v238 offset:16384
	ds_read_b128 v[166:169], v238 offset:17408
	ds_read_b128 v[170:173], v238 offset:18432
	ds_read_b128 v[174:177], v238 offset:19456
	ds_read_b128 v[178:181], v238 offset:20480
	ds_read_b128 v[182:185], v238 offset:21504
	ds_read_b128 v[202:205], v238 offset:22528
	ds_read_b128 v[206:209], v238 offset:23552
	global_load_lds_dwordx4 v[210:211], off
	s_add_i32 m0, s0, 0x2000
	s_add_u32 s20, s24, 0x160000
	v_lshl_add_u64 v[212:213], s[24:25], 0, v[196:197]
	s_addc_u32 s21, s25, 0
	s_add_i32 s0, s1, s31
	global_load_lds_dwordx4 v[212:213], off
	v_lshl_add_u64 v[214:215], s[20:21], 0, v[186:187]
	s_mov_b32 m0, s0
	v_lshl_add_u64 v[216:217], s[26:27], 0, v[194:195]
	global_load_lds_dwordx4 v[214:215], off
	v_lshl_add_u64 v[214:215], s[20:21], 0, v[196:197]
	s_add_i32 m0, s0, 0x2000
	s_nop 0
	global_load_lds_dwordx4 v[214:215], off
	v_lshl_add_u64 v[214:215], s[26:27], 0, v[192:193]
	s_mov_b32 m0, s34
	s_nop 0
	global_load_lds_dwordx4 v[214:215], off
	s_mov_b32 m0, s35
	s_nop 0
	global_load_lds_dwordx4 v[216:217], off
	s_waitcnt vmcnt(8)
	s_waitcnt lgkmcnt(0)
	s_setprio 1
	s_barrier

	v_mfma_f32_16x16x32_bf16 v[62:65], v[90:93], v[162:165], v[62:65]
	v_mfma_f32_16x16x32_bf16 v[58:61], v[114:117], v[162:165], v[58:61]
	v_mfma_f32_16x16x32_bf16 v[62:65], v[102:105], v[166:169], v[62:65]
	v_mfma_f32_16x16x32_bf16 v[58:61], v[126:129], v[166:169], v[58:61]
	v_mfma_f32_16x16x32_bf16 v[46:49], v[90:93], v[170:173], v[46:49]
	v_mfma_f32_16x16x32_bf16 v[42:45], v[114:117], v[170:173], v[42:45]
	v_mfma_f32_16x16x32_bf16 v[46:49], v[102:105], v[174:177], v[46:49]
	v_mfma_f32_16x16x32_bf16 v[42:45], v[126:129], v[174:177], v[42:45]
	v_mfma_f32_16x16x32_bf16 v[30:33], v[90:93], v[178:181], v[30:33]
	v_mfma_f32_16x16x32_bf16 v[26:29], v[114:117], v[178:181], v[26:29]
	v_mfma_f32_16x16x32_bf16 v[30:33], v[102:105], v[182:185], v[30:33]
	v_mfma_f32_16x16x32_bf16 v[26:29], v[126:129], v[182:185], v[26:29]
	v_mfma_f32_16x16x32_bf16 v[14:17], v[90:93], v[202:205], v[14:17]
	v_mfma_f32_16x16x32_bf16 v[10:13], v[114:117], v[202:205], v[10:13]
	v_mfma_f32_16x16x32_bf16 v[14:17], v[102:105], v[206:209], v[14:17]
	v_mfma_f32_16x16x32_bf16 v[10:13], v[126:129], v[206:209], v[10:13]


	v_mfma_f32_16x16x32_bf16 v[54:57], v[138:141], v[162:165], v[54:57]
	v_mfma_f32_16x16x32_bf16 v[50:53], v[154:157], v[162:165], v[50:53]
	v_mfma_f32_16x16x32_bf16 v[54:57], v[142:145], v[166:169], v[54:57]
	v_mfma_f32_16x16x32_bf16 v[50:53], v[158:161], v[166:169], v[50:53]
	v_mfma_f32_16x16x32_bf16 v[38:41], v[138:141], v[170:173], v[38:41]
	v_mfma_f32_16x16x32_bf16 v[34:37], v[154:157], v[170:173], v[34:37]
	v_mfma_f32_16x16x32_bf16 v[38:41], v[142:145], v[174:177], v[38:41]
	v_mfma_f32_16x16x32_bf16 v[34:37], v[158:161], v[174:177], v[34:37]
	v_mfma_f32_16x16x32_bf16 v[22:25], v[138:141], v[178:181], v[22:25]
	v_mfma_f32_16x16x32_bf16 v[18:21], v[154:157], v[178:181], v[18:21]
	v_mfma_f32_16x16x32_bf16 v[22:25], v[142:145], v[182:185], v[22:25]
	v_mfma_f32_16x16x32_bf16 v[18:21], v[158:161], v[182:185], v[18:21]
	v_mfma_f32_16x16x32_bf16 v[6:9], v[138:141], v[202:205], v[6:9]
	v_mfma_f32_16x16x32_bf16 v[2:5], v[154:157], v[202:205], v[2:5]
	v_mfma_f32_16x16x32_bf16 v[6:9], v[142:145], v[206:209], v[6:9]
	v_mfma_f32_16x16x32_bf16 v[2:5], v[158:161], v[206:209], v[2:5]
	s_barrier
	s_setprio 0
	s_add_i32 s0, 0, 0x18000
	s_add_i32 s1, 0, 0x1c000
	v_add_u32_e32 v126, s0, v237
	v_add_u32_e32 v158, s1, v237
	ds_read_b128 v[90:93], v126
	ds_read_b128 v[102:105], v126 offset:1024
	ds_read_b128 v[114:117], v126 offset:2048
	ds_read_b128 v[126:129], v126 offset:3072
	ds_read_b128 v[138:141], v158
	ds_read_b128 v[142:145], v158 offset:1024
	ds_read_b128 v[154:157], v158 offset:2048
	ds_read_b128 v[158:161], v158 offset:3072
	s_add_u32 s20, s26, 0x160000
	s_addc_u32 s21, s27, 0
	s_mov_b32 m0, s36
	v_lshl_add_u64 v[218:219], s[20:21], 0, v[192:193]
	ds_read_b128 v[162:165], v238 offset:32768
	ds_read_b128 v[166:169], v238 offset:33792
	ds_read_b128 v[170:173], v238 offset:34816
	ds_read_b128 v[174:177], v238 offset:35840
	ds_read_b128 v[178:181], v238 offset:36864
	ds_read_b128 v[182:185], v238 offset:37888
	ds_read_b128 v[202:205], v238 offset:38912
	ds_read_b128 v[206:209], v238 offset:39936
	global_load_lds_dwordx4 v[218:219], off
	v_lshl_add_u64 v[218:219], s[20:21], 0, v[194:195]
	s_mov_b32 m0, s37
	s_nop 0
	global_load_lds_dwordx4 v[218:219], off
	s_waitcnt vmcnt(8)
	s_waitcnt lgkmcnt(0)
	s_setprio 1
	s_barrier

	v_mfma_f32_16x16x32_bf16 v[150:153], v[90:93], v[162:165], v[150:153]
	v_mfma_f32_16x16x32_bf16 v[146:149], v[114:117], v[162:165], v[146:149]
	v_mfma_f32_16x16x32_bf16 v[150:153], v[102:105], v[166:169], v[150:153]
	v_mfma_f32_16x16x32_bf16 v[146:149], v[126:129], v[166:169], v[146:149]
	v_mfma_f32_16x16x32_bf16 v[122:125], v[90:93], v[170:173], v[122:125]
	v_mfma_f32_16x16x32_bf16 v[118:121], v[114:117], v[170:173], v[118:121]
	v_mfma_f32_16x16x32_bf16 v[122:125], v[102:105], v[174:177], v[122:125]
	v_mfma_f32_16x16x32_bf16 v[118:121], v[126:129], v[174:177], v[118:121]
	v_mfma_f32_16x16x32_bf16 v[98:101], v[90:93], v[178:181], v[98:101]
	v_mfma_f32_16x16x32_bf16 v[94:97], v[114:117], v[178:181], v[94:97]
	v_mfma_f32_16x16x32_bf16 v[98:101], v[102:105], v[182:185], v[98:101]
	v_mfma_f32_16x16x32_bf16 v[94:97], v[126:129], v[182:185], v[94:97]
	v_mfma_f32_16x16x32_bf16 v[78:81], v[90:93], v[202:205], v[78:81]
	v_mfma_f32_16x16x32_bf16 v[74:77], v[114:117], v[202:205], v[74:77]
	v_mfma_f32_16x16x32_bf16 v[78:81], v[102:105], v[206:209], v[78:81]
	v_mfma_f32_16x16x32_bf16 v[74:77], v[126:129], v[206:209], v[74:77]


	v_mfma_f32_16x16x32_bf16 v[134:137], v[138:141], v[162:165], v[134:137]
	v_mfma_f32_16x16x32_bf16 v[130:133], v[154:157], v[162:165], v[130:133]
	v_mfma_f32_16x16x32_bf16 v[134:137], v[142:145], v[166:169], v[134:137]
	v_mfma_f32_16x16x32_bf16 v[130:133], v[158:161], v[166:169], v[130:133]
	v_mfma_f32_16x16x32_bf16 v[110:113], v[138:141], v[170:173], v[110:113]
	v_mfma_f32_16x16x32_bf16 v[106:109], v[154:157], v[170:173], v[106:109]
	v_mfma_f32_16x16x32_bf16 v[110:113], v[142:145], v[174:177], v[110:113]
	v_mfma_f32_16x16x32_bf16 v[106:109], v[158:161], v[174:177], v[106:109]
	v_mfma_f32_16x16x32_bf16 v[86:89], v[138:141], v[178:181], v[86:89]
	v_mfma_f32_16x16x32_bf16 v[82:85], v[154:157], v[178:181], v[82:85]
	v_mfma_f32_16x16x32_bf16 v[86:89], v[142:145], v[182:185], v[86:89]
	v_mfma_f32_16x16x32_bf16 v[82:85], v[158:161], v[182:185], v[82:85]
	v_mfma_f32_16x16x32_bf16 v[70:73], v[138:141], v[202:205], v[70:73]
	v_mfma_f32_16x16x32_bf16 v[66:69], v[154:157], v[202:205], v[66:69]
	v_mfma_f32_16x16x32_bf16 v[70:73], v[142:145], v[206:209], v[70:73]
	v_mfma_f32_16x16x32_bf16 v[66:69], v[158:161], v[206:209], v[66:69]
	s_barrier
	s_setprio 0
	s_add_i32 s0, s0, s31
	v_lshl_add_u64 v[210:211], v[210:211], 0, s[84:85]
	s_mov_b32 m0, s0
	ds_read_b128 v[162:165], v238 offset:49152
	ds_read_b128 v[166:169], v238 offset:50176
	ds_read_b128 v[170:173], v238 offset:51200
	ds_read_b128 v[174:177], v238 offset:52224
	ds_read_b128 v[178:181], v238 offset:53248
	ds_read_b128 v[182:185], v238 offset:54272
	ds_read_b128 v[202:205], v238 offset:55296
	ds_read_b128 v[206:209], v238 offset:56320
	global_load_lds_dwordx4 v[210:211], off
	s_add_i32 m0, s0, 0x2000
	s_add_u32 s20, s24, 0x160080
	v_lshl_add_u64 v[210:211], v[212:213], 0, s[84:85]
	s_addc_u32 s21, s25, 0
	s_add_i32 s0, s1, s31
	global_load_lds_dwordx4 v[210:211], off
	v_lshl_add_u64 v[210:211], s[20:21], 0, v[186:187]
	s_mov_b32 m0, s0
	s_nop 0
	global_load_lds_dwordx4 v[210:211], off
	v_lshl_add_u64 v[210:211], s[20:21], 0, v[196:197]
	s_add_i32 m0, s0, 0x2000
	s_nop 0
	global_load_lds_dwordx4 v[210:211], off
	v_lshl_add_u64 v[210:211], v[214:215], 0, s[84:85]
	s_mov_b32 m0, s41
	s_nop 0
	global_load_lds_dwordx4 v[210:211], off
	v_lshl_add_u64 v[210:211], v[216:217], 0, s[84:85]
	s_mov_b32 m0, s42
	s_nop 0
	global_load_lds_dwordx4 v[210:211], off
	s_waitcnt vmcnt(8)
	s_waitcnt lgkmcnt(0)
	s_setprio 1
	s_barrier

	v_mfma_f32_16x16x32_bf16 v[62:65], v[90:93], v[162:165], v[62:65]
	v_mfma_f32_16x16x32_bf16 v[58:61], v[114:117], v[162:165], v[58:61]
	v_mfma_f32_16x16x32_bf16 v[62:65], v[102:105], v[166:169], v[62:65]
	v_mfma_f32_16x16x32_bf16 v[58:61], v[126:129], v[166:169], v[58:61]
	v_mfma_f32_16x16x32_bf16 v[46:49], v[90:93], v[170:173], v[46:49]
	v_mfma_f32_16x16x32_bf16 v[42:45], v[114:117], v[170:173], v[42:45]
	v_mfma_f32_16x16x32_bf16 v[46:49], v[102:105], v[174:177], v[46:49]
	v_mfma_f32_16x16x32_bf16 v[42:45], v[126:129], v[174:177], v[42:45]
	v_mfma_f32_16x16x32_bf16 v[30:33], v[90:93], v[178:181], v[30:33]
	v_mfma_f32_16x16x32_bf16 v[26:29], v[114:117], v[178:181], v[26:29]
	v_mfma_f32_16x16x32_bf16 v[30:33], v[102:105], v[182:185], v[30:33]
	v_mfma_f32_16x16x32_bf16 v[26:29], v[126:129], v[182:185], v[26:29]
	v_mfma_f32_16x16x32_bf16 v[14:17], v[90:93], v[202:205], v[14:17]
	v_mfma_f32_16x16x32_bf16 v[10:13], v[114:117], v[202:205], v[10:13]
	v_mfma_f32_16x16x32_bf16 v[14:17], v[102:105], v[206:209], v[14:17]
	v_mfma_f32_16x16x32_bf16 v[10:13], v[126:129], v[206:209], v[10:13]


	v_mfma_f32_16x16x32_bf16 v[54:57], v[138:141], v[162:165], v[54:57]
	v_mfma_f32_16x16x32_bf16 v[50:53], v[154:157], v[162:165], v[50:53]
	v_mfma_f32_16x16x32_bf16 v[54:57], v[142:145], v[166:169], v[54:57]
	v_mfma_f32_16x16x32_bf16 v[50:53], v[158:161], v[166:169], v[50:53]
	v_mfma_f32_16x16x32_bf16 v[38:41], v[138:141], v[170:173], v[38:41]
	v_mfma_f32_16x16x32_bf16 v[34:37], v[154:157], v[170:173], v[34:37]
	v_mfma_f32_16x16x32_bf16 v[38:41], v[142:145], v[174:177], v[38:41]
	v_mfma_f32_16x16x32_bf16 v[34:37], v[158:161], v[174:177], v[34:37]
	v_mfma_f32_16x16x32_bf16 v[22:25], v[138:141], v[178:181], v[22:25]
	v_mfma_f32_16x16x32_bf16 v[18:21], v[154:157], v[178:181], v[18:21]
	v_mfma_f32_16x16x32_bf16 v[22:25], v[142:145], v[182:185], v[22:25]
	v_mfma_f32_16x16x32_bf16 v[18:21], v[158:161], v[182:185], v[18:21]
	v_mfma_f32_16x16x32_bf16 v[6:9], v[138:141], v[202:205], v[6:9]
	v_mfma_f32_16x16x32_bf16 v[2:5], v[154:157], v[202:205], v[2:5]
	v_mfma_f32_16x16x32_bf16 v[6:9], v[142:145], v[206:209], v[6:9]
	v_mfma_f32_16x16x32_bf16 v[2:5], v[158:161], v[206:209], v[2:5]
	s_barrier
	s_setprio 0
	s_add_i32 s51, s51, 2
	s_add_u32 s49, s49, 0x100
	s_addc_u32 s50, s50, 0
	s_cmpk_gt_u32 s51, 0x55
	s_mov_b64 s[20:21], s[22:23]
	s_cbranch_scc0 .LBB0_243
	s_and_b64 vcc, exec, s[16:17]
	s_cbranch_vccz .LBB0_246
	s_barrier

.LBB0_443:
	s_add_u32 s0, s26, 0xfff80080
	s_addc_u32 s1, s27, -1
	s_add_i32 s56, 0, 0x10000
	s_cmp_eq_u32 s55, 28
	s_cselect_b32 s31, s19, s1
	s_cselect_b32 s30, s51, s0
	v_add_u32_e32 v140, s56, v144
	s_cselect_b32 s29, s17, s54
	s_cselect_b32 s28, s52, s53
	s_add_i32 s0, 0, 0x14000
	ds_read_b128 v[146:149], v140
	ds_read_b128 v[150:153], v140 offset:1024
	ds_read_b128 v[154:157], v140 offset:2048
	ds_read_b128 v[158:161], v140 offset:3072
	v_add_u32_e32 v140, s0, v144
	ds_read_b128 v[162:165], v140
	ds_read_b128 v[166:169], v140 offset:1024
	ds_read_b128 v[170:173], v140 offset:2048
	ds_read_b128 v[174:177], v140 offset:3072
	v_lshl_add_u64 v[140:141], s[26:27], 0, v[136:137]
	s_add_i32 m0, s25, 0xc000
	ds_read_b128 v[178:181], v145
	ds_read_b128 v[182:185], v145 offset:1024
	ds_read_b128 v[192:195], v145 offset:2048
	ds_read_b128 v[196:199], v145 offset:3072
	ds_read_b128 v[200:203], v145 offset:4096
	ds_read_b128 v[204:207], v145 offset:5120
	ds_read_b128 v[208:211], v145 offset:6144
	ds_read_b128 v[212:215], v145 offset:7168
	global_load_lds_dwordx4 v[140:141], off
	v_lshl_add_u64 v[140:141], s[26:27], 0, v[138:139]
	s_add_i32 m0, s25, 0xe000
	s_nop 0
	global_load_lds_dwordx4 v[140:141], off
	s_waitcnt vmcnt(8)
	s_waitcnt lgkmcnt(0)
	s_setprio 1
	s_barrier

	v_mfma_f32_16x16x32_bf16 v[126:129], v[146:149], v[178:181], v[126:129]
	v_mfma_f32_16x16x32_bf16 v[122:125], v[154:157], v[178:181], v[122:125]
	v_mfma_f32_16x16x32_bf16 v[126:129], v[150:153], v[182:185], v[126:129]
	v_mfma_f32_16x16x32_bf16 v[122:125], v[158:161], v[182:185], v[122:125]
	v_mfma_f32_16x16x32_bf16 v[114:117], v[146:149], v[192:195], v[114:117]
	v_mfma_f32_16x16x32_bf16 v[106:109], v[154:157], v[192:195], v[106:109]
	v_mfma_f32_16x16x32_bf16 v[114:117], v[150:153], v[196:199], v[114:117]
	v_mfma_f32_16x16x32_bf16 v[106:109], v[158:161], v[196:199], v[106:109]
	v_mfma_f32_16x16x32_bf16 v[98:101], v[146:149], v[200:203], v[98:101]
	v_mfma_f32_16x16x32_bf16 v[90:93], v[154:157], v[200:203], v[90:93]
	v_mfma_f32_16x16x32_bf16 v[98:101], v[150:153], v[204:207], v[98:101]
	v_mfma_f32_16x16x32_bf16 v[90:93], v[158:161], v[204:207], v[90:93]
	v_mfma_f32_16x16x32_bf16 v[82:85], v[146:149], v[208:211], v[82:85]
	v_mfma_f32_16x16x32_bf16 v[74:77], v[154:157], v[208:211], v[74:77]
	v_mfma_f32_16x16x32_bf16 v[82:85], v[150:153], v[212:215], v[82:85]
	v_mfma_f32_16x16x32_bf16 v[74:77], v[158:161], v[212:215], v[74:77]


	v_mfma_f32_16x16x32_bf16 v[118:121], v[162:165], v[178:181], v[118:121]
	v_mfma_f32_16x16x32_bf16 v[110:113], v[170:173], v[178:181], v[110:113]
	v_mfma_f32_16x16x32_bf16 v[118:121], v[166:169], v[182:185], v[118:121]
	v_mfma_f32_16x16x32_bf16 v[110:113], v[174:177], v[182:185], v[110:113]
	v_mfma_f32_16x16x32_bf16 v[102:105], v[162:165], v[192:195], v[102:105]
	v_mfma_f32_16x16x32_bf16 v[94:97], v[170:173], v[192:195], v[94:97]
	v_mfma_f32_16x16x32_bf16 v[102:105], v[166:169], v[196:199], v[102:105]
	v_mfma_f32_16x16x32_bf16 v[94:97], v[174:177], v[196:199], v[94:97]
	v_mfma_f32_16x16x32_bf16 v[86:89], v[162:165], v[200:203], v[86:89]
	v_mfma_f32_16x16x32_bf16 v[78:81], v[170:173], v[200:203], v[78:81]
	v_mfma_f32_16x16x32_bf16 v[86:89], v[166:169], v[204:207], v[86:89]
	v_mfma_f32_16x16x32_bf16 v[78:81], v[174:177], v[204:207], v[78:81]
	v_mfma_f32_16x16x32_bf16 v[70:73], v[162:165], v[208:211], v[70:73]
	v_mfma_f32_16x16x32_bf16 v[66:69], v[170:173], v[208:211], v[66:69]
	v_mfma_f32_16x16x32_bf16 v[70:73], v[166:169], v[212:215], v[70:73]
	v_mfma_f32_16x16x32_bf16 v[66:69], v[174:177], v[212:215], v[66:69]
	s_barrier
	s_setprio 0
	s_add_i32 s1, s56, s39
	v_lshl_add_u64 v[140:141], s[28:29], 0, v[186:187]
	s_mov_b32 m0, s1
	ds_read_b128 v[178:181], v145 offset:16384
	ds_read_b128 v[182:185], v145 offset:17408
	ds_read_b128 v[192:195], v145 offset:18432
	ds_read_b128 v[196:199], v145 offset:19456
	ds_read_b128 v[200:203], v145 offset:20480
	ds_read_b128 v[204:207], v145 offset:21504
	ds_read_b128 v[208:211], v145 offset:22528
	ds_read_b128 v[212:215], v145 offset:23552
	global_load_lds_dwordx4 v[140:141], off
	s_add_i32 m0, s1, 0x2000
	s_add_u32 s56, s28, 0x80000
	v_lshl_add_u64 v[188:189], s[28:29], 0, v[130:131]
	s_addc_u32 s57, s29, 0
	s_add_i32 s0, s0, s39
	global_load_lds_dwordx4 v[188:189], off
	v_lshl_add_u64 v[216:217], s[56:57], 0, v[186:187]
	s_mov_b32 m0, s0
	v_lshl_add_u64 v[218:219], s[30:31], 0, v[132:133]
	global_load_lds_dwordx4 v[216:217], off
	v_lshl_add_u64 v[216:217], s[56:57], 0, v[130:131]
	s_add_i32 m0, s0, 0x2000
	s_nop 0
	global_load_lds_dwordx4 v[216:217], off
	v_lshl_add_u64 v[216:217], s[30:31], 0, v[134:135]
	s_mov_b32 m0, s25
	s_nop 0
	global_load_lds_dwordx4 v[216:217], off
	s_mov_b32 m0, s40
	s_nop 0
	global_load_lds_dwordx4 v[218:219], off
	s_waitcnt vmcnt(8)
	s_waitcnt lgkmcnt(0)
	s_setprio 1
	s_barrier

	v_mfma_f32_16x16x32_bf16 v[62:65], v[146:149], v[178:181], v[62:65]
	v_mfma_f32_16x16x32_bf16 v[58:61], v[154:157], v[178:181], v[58:61]
	v_mfma_f32_16x16x32_bf16 v[62:65], v[150:153], v[182:185], v[62:65]
	v_mfma_f32_16x16x32_bf16 v[58:61], v[158:161], v[182:185], v[58:61]
	v_mfma_f32_16x16x32_bf16 v[50:53], v[146:149], v[192:195], v[50:53]
	v_mfma_f32_16x16x32_bf16 v[42:45], v[154:157], v[192:195], v[42:45]
	v_mfma_f32_16x16x32_bf16 v[50:53], v[150:153], v[196:199], v[50:53]
	v_mfma_f32_16x16x32_bf16 v[42:45], v[158:161], v[196:199], v[42:45]
	v_mfma_f32_16x16x32_bf16 v[34:37], v[146:149], v[200:203], v[34:37]
	v_mfma_f32_16x16x32_bf16 v[26:29], v[154:157], v[200:203], v[26:29]
	v_mfma_f32_16x16x32_bf16 v[34:37], v[150:153], v[204:207], v[34:37]
	v_mfma_f32_16x16x32_bf16 v[26:29], v[158:161], v[204:207], v[26:29]
	v_mfma_f32_16x16x32_bf16 v[18:21], v[146:149], v[208:211], v[18:21]
	v_mfma_f32_16x16x32_bf16 v[10:13], v[154:157], v[208:211], v[10:13]
	v_mfma_f32_16x16x32_bf16 v[18:21], v[150:153], v[212:215], v[18:21]
	v_mfma_f32_16x16x32_bf16 v[10:13], v[158:161], v[212:215], v[10:13]


	v_mfma_f32_16x16x32_bf16 v[54:57], v[162:165], v[178:181], v[54:57]
	v_mfma_f32_16x16x32_bf16 v[46:49], v[170:173], v[178:181], v[46:49]
	v_mfma_f32_16x16x32_bf16 v[54:57], v[166:169], v[182:185], v[54:57]
	v_mfma_f32_16x16x32_bf16 v[46:49], v[174:177], v[182:185], v[46:49]
	v_mfma_f32_16x16x32_bf16 v[38:41], v[162:165], v[192:195], v[38:41]
	v_mfma_f32_16x16x32_bf16 v[30:33], v[170:173], v[192:195], v[30:33]
	v_mfma_f32_16x16x32_bf16 v[38:41], v[166:169], v[196:199], v[38:41]
	v_mfma_f32_16x16x32_bf16 v[30:33], v[174:177], v[196:199], v[30:33]
	v_mfma_f32_16x16x32_bf16 v[22:25], v[162:165], v[200:203], v[22:25]
	v_mfma_f32_16x16x32_bf16 v[14:17], v[170:173], v[200:203], v[14:17]
	v_mfma_f32_16x16x32_bf16 v[22:25], v[166:169], v[204:207], v[22:25]
	v_mfma_f32_16x16x32_bf16 v[14:17], v[174:177], v[204:207], v[14:17]
	v_mfma_f32_16x16x32_bf16 v[6:9], v[162:165], v[208:211], v[6:9]
	v_mfma_f32_16x16x32_bf16 v[2:5], v[170:173], v[208:211], v[2:5]
	v_mfma_f32_16x16x32_bf16 v[6:9], v[166:169], v[212:215], v[6:9]
	v_mfma_f32_16x16x32_bf16 v[2:5], v[174:177], v[212:215], v[2:5]
	s_barrier
	s_setprio 0
	s_add_i32 s0, 0, 0x18000
	s_add_i32 s1, 0, 0x1c000
	v_add_u32_e32 v158, s0, v144
	v_add_u32_e32 v174, s1, v144
	ds_read_b128 v[146:149], v158
	ds_read_b128 v[150:153], v158 offset:1024
	ds_read_b128 v[154:157], v158 offset:2048
	ds_read_b128 v[158:161], v158 offset:3072
	ds_read_b128 v[162:165], v174
	ds_read_b128 v[166:169], v174 offset:1024
	ds_read_b128 v[170:173], v174 offset:2048
	ds_read_b128 v[174:177], v174 offset:3072
	s_add_u32 s30, s30, 0x80000
	s_addc_u32 s31, s31, 0
	s_mov_b32 m0, s41
	v_lshl_add_u64 v[220:221], s[30:31], 0, v[134:135]
	ds_read_b128 v[178:181], v145 offset:32768
	ds_read_b128 v[182:185], v145 offset:33792
	ds_read_b128 v[192:195], v145 offset:34816
	ds_read_b128 v[196:199], v145 offset:35840
	ds_read_b128 v[200:203], v145 offset:36864
	ds_read_b128 v[204:207], v145 offset:37888
	ds_read_b128 v[208:211], v145 offset:38912
	ds_read_b128 v[212:215], v145 offset:39936
	global_load_lds_dwordx4 v[220:221], off
	v_lshl_add_u64 v[220:221], s[30:31], 0, v[132:133]
	s_mov_b32 m0, s42
	s_nop 0
	global_load_lds_dwordx4 v[220:221], off
	s_waitcnt vmcnt(8)
	s_waitcnt lgkmcnt(0)
	s_setprio 1
	s_barrier

	v_mfma_f32_16x16x32_bf16 v[126:129], v[146:149], v[178:181], v[126:129]
	v_mfma_f32_16x16x32_bf16 v[122:125], v[154:157], v[178:181], v[122:125]
	v_mfma_f32_16x16x32_bf16 v[126:129], v[150:153], v[182:185], v[126:129]
	v_mfma_f32_16x16x32_bf16 v[122:125], v[158:161], v[182:185], v[122:125]
	v_mfma_f32_16x16x32_bf16 v[114:117], v[146:149], v[192:195], v[114:117]
	v_mfma_f32_16x16x32_bf16 v[106:109], v[154:157], v[192:195], v[106:109]
	v_mfma_f32_16x16x32_bf16 v[114:117], v[150:153], v[196:199], v[114:117]
	v_mfma_f32_16x16x32_bf16 v[106:109], v[158:161], v[196:199], v[106:109]
	v_mfma_f32_16x16x32_bf16 v[98:101], v[146:149], v[200:203], v[98:101]
	v_mfma_f32_16x16x32_bf16 v[90:93], v[154:157], v[200:203], v[90:93]
	v_mfma_f32_16x16x32_bf16 v[98:101], v[150:153], v[204:207], v[98:101]
	v_mfma_f32_16x16x32_bf16 v[90:93], v[158:161], v[204:207], v[90:93]
	v_mfma_f32_16x16x32_bf16 v[82:85], v[146:149], v[208:211], v[82:85]
	v_mfma_f32_16x16x32_bf16 v[74:77], v[154:157], v[208:211], v[74:77]
	v_mfma_f32_16x16x32_bf16 v[82:85], v[150:153], v[212:215], v[82:85]
	v_mfma_f32_16x16x32_bf16 v[74:77], v[158:161], v[212:215], v[74:77]


	v_mfma_f32_16x16x32_bf16 v[118:121], v[162:165], v[178:181], v[118:121]
	v_mfma_f32_16x16x32_bf16 v[110:113], v[170:173], v[178:181], v[110:113]
	v_mfma_f32_16x16x32_bf16 v[118:121], v[166:169], v[182:185], v[118:121]
	v_mfma_f32_16x16x32_bf16 v[110:113], v[174:177], v[182:185], v[110:113]
	v_mfma_f32_16x16x32_bf16 v[102:105], v[162:165], v[192:195], v[102:105]
	v_mfma_f32_16x16x32_bf16 v[94:97], v[170:173], v[192:195], v[94:97]
	v_mfma_f32_16x16x32_bf16 v[102:105], v[166:169], v[196:199], v[102:105]
	v_mfma_f32_16x16x32_bf16 v[94:97], v[174:177], v[196:199], v[94:97]
	v_mfma_f32_16x16x32_bf16 v[86:89], v[162:165], v[200:203], v[86:89]
	v_mfma_f32_16x16x32_bf16 v[78:81], v[170:173], v[200:203], v[78:81]
	v_mfma_f32_16x16x32_bf16 v[86:89], v[166:169], v[204:207], v[86:89]
	v_mfma_f32_16x16x32_bf16 v[78:81], v[174:177], v[204:207], v[78:81]
	v_mfma_f32_16x16x32_bf16 v[70:73], v[162:165], v[208:211], v[70:73]
	v_mfma_f32_16x16x32_bf16 v[66:69], v[170:173], v[208:211], v[66:69]
	v_mfma_f32_16x16x32_bf16 v[70:73], v[166:169], v[212:215], v[70:73]
	v_mfma_f32_16x16x32_bf16 v[66:69], v[174:177], v[212:215], v[66:69]
	s_barrier
	s_setprio 0
	s_add_i32 s0, s0, s39
	v_lshl_add_u64 v[140:141], v[140:141], 0, s[84:85]
	s_mov_b32 m0, s0
	ds_read_b128 v[178:181], v145 offset:49152
	ds_read_b128 v[182:185], v145 offset:50176
	ds_read_b128 v[192:195], v145 offset:51200
	ds_read_b128 v[196:199], v145 offset:52224
	ds_read_b128 v[200:203], v145 offset:53248
	ds_read_b128 v[204:207], v145 offset:54272
	ds_read_b128 v[208:211], v145 offset:55296
	ds_read_b128 v[212:215], v145 offset:56320
	global_load_lds_dwordx4 v[140:141], off
	s_add_i32 m0, s0, 0x2000
	s_add_u32 s28, s28, 0x80080
	v_lshl_add_u64 v[140:141], v[188:189], 0, s[84:85]
	s_addc_u32 s29, s29, 0
	s_add_i32 s0, s1, s39
	global_load_lds_dwordx4 v[140:141], off
	v_lshl_add_u64 v[140:141], s[28:29], 0, v[186:187]
	s_mov_b32 m0, s0
	s_nop 0
	global_load_lds_dwordx4 v[140:141], off
	v_lshl_add_u64 v[140:141], s[28:29], 0, v[130:131]
	s_add_i32 m0, s0, 0x2000
	s_nop 0
	global_load_lds_dwordx4 v[140:141], off
	v_lshl_add_u64 v[140:141], v[216:217], 0, s[84:85]
	s_mov_b32 m0, s43
	s_nop 0
	global_load_lds_dwordx4 v[140:141], off
	v_lshl_add_u64 v[140:141], v[218:219], 0, s[84:85]
	s_mov_b32 m0, s44
	s_nop 0
	global_load_lds_dwordx4 v[140:141], off
	s_waitcnt vmcnt(8)
	s_waitcnt lgkmcnt(0)
	s_setprio 1
	s_barrier

	v_mfma_f32_16x16x32_bf16 v[62:65], v[146:149], v[178:181], v[62:65]
	v_mfma_f32_16x16x32_bf16 v[58:61], v[154:157], v[178:181], v[58:61]
	v_mfma_f32_16x16x32_bf16 v[62:65], v[150:153], v[182:185], v[62:65]
	v_mfma_f32_16x16x32_bf16 v[58:61], v[158:161], v[182:185], v[58:61]
	v_mfma_f32_16x16x32_bf16 v[50:53], v[146:149], v[192:195], v[50:53]
	v_mfma_f32_16x16x32_bf16 v[42:45], v[154:157], v[192:195], v[42:45]
	v_mfma_f32_16x16x32_bf16 v[50:53], v[150:153], v[196:199], v[50:53]
	v_mfma_f32_16x16x32_bf16 v[42:45], v[158:161], v[196:199], v[42:45]
	v_mfma_f32_16x16x32_bf16 v[34:37], v[146:149], v[200:203], v[34:37]
	v_mfma_f32_16x16x32_bf16 v[26:29], v[154:157], v[200:203], v[26:29]
	v_mfma_f32_16x16x32_bf16 v[34:37], v[150:153], v[204:207], v[34:37]
	v_mfma_f32_16x16x32_bf16 v[26:29], v[158:161], v[204:207], v[26:29]
	v_mfma_f32_16x16x32_bf16 v[18:21], v[146:149], v[208:211], v[18:21]
	v_mfma_f32_16x16x32_bf16 v[10:13], v[154:157], v[208:211], v[10:13]
	v_mfma_f32_16x16x32_bf16 v[18:21], v[150:153], v[212:215], v[18:21]
	v_mfma_f32_16x16x32_bf16 v[10:13], v[158:161], v[212:215], v[10:13]


	v_mfma_f32_16x16x32_bf16 v[54:57], v[162:165], v[178:181], v[54:57]
	v_mfma_f32_16x16x32_bf16 v[46:49], v[170:173], v[178:181], v[46:49]
	v_mfma_f32_16x16x32_bf16 v[54:57], v[166:169], v[182:185], v[54:57]
	v_mfma_f32_16x16x32_bf16 v[46:49], v[174:177], v[182:185], v[46:49]
	v_mfma_f32_16x16x32_bf16 v[38:41], v[162:165], v[192:195], v[38:41]
	v_mfma_f32_16x16x32_bf16 v[30:33], v[170:173], v[192:195], v[30:33]
	v_mfma_f32_16x16x32_bf16 v[38:41], v[166:169], v[196:199], v[38:41]
	v_mfma_f32_16x16x32_bf16 v[30:33], v[174:177], v[196:199], v[30:33]
	v_mfma_f32_16x16x32_bf16 v[22:25], v[162:165], v[200:203], v[22:25]
	v_mfma_f32_16x16x32_bf16 v[14:17], v[170:173], v[200:203], v[14:17]
	v_mfma_f32_16x16x32_bf16 v[22:25], v[166:169], v[204:207], v[22:25]
	v_mfma_f32_16x16x32_bf16 v[14:17], v[174:177], v[204:207], v[14:17]
	v_mfma_f32_16x16x32_bf16 v[6:9], v[162:165], v[208:211], v[6:9]
	v_mfma_f32_16x16x32_bf16 v[2:5], v[170:173], v[208:211], v[2:5]
	v_mfma_f32_16x16x32_bf16 v[6:9], v[166:169], v[212:215], v[6:9]
	v_mfma_f32_16x16x32_bf16 v[2:5], v[174:177], v[212:215], v[2:5]
	s_barrier
	s_setprio 0
	s_add_i32 s55, s55, 2
	s_add_u32 s26, s26, 0x100
	s_addc_u32 s27, s27, 0
	s_add_u32 s53, s53, 0x100
	s_addc_u32 s54, s54, 0
	s_cmp_gt_u32 s55, 29
	s_cbranch_scc0 .LBB0_443
	s_and_b64 vcc, exec, s[14:15]
	s_cbranch_vccz .LBB0_446
	s_barrier

.LBB0_1126:
	s_add_u32 s0, s28, 0xfff80080
	s_addc_u32 s1, s29, -1
	s_add_i32 s54, 0, 0x10000
	s_cmp_eq_u32 s53, 28
	s_cselect_b32 s35, s19, s1
	s_cselect_b32 s34, s25, s0
	s_cselect_b32 s31, s17, s52
	s_cselect_b32 s30, s27, s51
	s_add_i32 s55, 0, 0x14000
	v_add_u32_e32 v126, s54, v237
	v_add_u32_e32 v158, s55, v237
	ds_read_b128 v[90:93], v126
	ds_read_b128 v[102:105], v126 offset:1024
	ds_read_b128 v[114:117], v126 offset:2048
	ds_read_b128 v[126:129], v126 offset:3072
	ds_read_b128 v[138:141], v158
	ds_read_b128 v[142:145], v158 offset:1024
	ds_read_b128 v[154:157], v158 offset:2048
	ds_read_b128 v[158:161], v158 offset:3072
	v_lshl_add_u64 v[188:189], s[28:29], 0, v[198:199]
	s_add_i32 m0, s40, 0xc000
	ds_read_b128 v[162:165], v238
	ds_read_b128 v[166:169], v238 offset:1024
	ds_read_b128 v[170:173], v238 offset:2048
	ds_read_b128 v[174:177], v238 offset:3072
	ds_read_b128 v[178:181], v238 offset:4096
	ds_read_b128 v[182:185], v238 offset:5120
	ds_read_b128 v[202:205], v238 offset:6144
	ds_read_b128 v[206:209], v238 offset:7168
	global_load_lds_dwordx4 v[188:189], off
	v_lshl_add_u64 v[188:189], s[28:29], 0, v[200:201]
	s_add_i32 m0, s40, 0xe000
	s_nop 0
	global_load_lds_dwordx4 v[188:189], off
	s_waitcnt vmcnt(8)
	s_waitcnt lgkmcnt(0)
	s_setprio 1
	s_barrier

	v_mfma_f32_16x16x32_bf16 v[150:153], v[90:93], v[162:165], v[150:153]
	v_mfma_f32_16x16x32_bf16 v[146:149], v[114:117], v[162:165], v[146:149]
	v_mfma_f32_16x16x32_bf16 v[150:153], v[102:105], v[166:169], v[150:153]
	v_mfma_f32_16x16x32_bf16 v[146:149], v[126:129], v[166:169], v[146:149]
	v_mfma_f32_16x16x32_bf16 v[122:125], v[90:93], v[170:173], v[122:125]
	v_mfma_f32_16x16x32_bf16 v[118:121], v[114:117], v[170:173], v[118:121]
	v_mfma_f32_16x16x32_bf16 v[122:125], v[102:105], v[174:177], v[122:125]
	v_mfma_f32_16x16x32_bf16 v[118:121], v[126:129], v[174:177], v[118:121]
	v_mfma_f32_16x16x32_bf16 v[98:101], v[90:93], v[178:181], v[98:101]
	v_mfma_f32_16x16x32_bf16 v[94:97], v[114:117], v[178:181], v[94:97]
	v_mfma_f32_16x16x32_bf16 v[98:101], v[102:105], v[182:185], v[98:101]
	v_mfma_f32_16x16x32_bf16 v[94:97], v[126:129], v[182:185], v[94:97]
	v_mfma_f32_16x16x32_bf16 v[78:81], v[90:93], v[202:205], v[78:81]
	v_mfma_f32_16x16x32_bf16 v[74:77], v[114:117], v[202:205], v[74:77]
	v_mfma_f32_16x16x32_bf16 v[78:81], v[102:105], v[206:209], v[78:81]
	v_mfma_f32_16x16x32_bf16 v[74:77], v[126:129], v[206:209], v[74:77]


	v_mfma_f32_16x16x32_bf16 v[134:137], v[138:141], v[162:165], v[134:137]
	v_mfma_f32_16x16x32_bf16 v[130:133], v[154:157], v[162:165], v[130:133]
	v_mfma_f32_16x16x32_bf16 v[134:137], v[142:145], v[166:169], v[134:137]
	v_mfma_f32_16x16x32_bf16 v[130:133], v[158:161], v[166:169], v[130:133]
	v_mfma_f32_16x16x32_bf16 v[110:113], v[138:141], v[170:173], v[110:113]
	v_mfma_f32_16x16x32_bf16 v[106:109], v[154:157], v[170:173], v[106:109]
	v_mfma_f32_16x16x32_bf16 v[110:113], v[142:145], v[174:177], v[110:113]
	v_mfma_f32_16x16x32_bf16 v[106:109], v[158:161], v[174:177], v[106:109]
	v_mfma_f32_16x16x32_bf16 v[86:89], v[138:141], v[178:181], v[86:89]
	v_mfma_f32_16x16x32_bf16 v[82:85], v[154:157], v[178:181], v[82:85]
	v_mfma_f32_16x16x32_bf16 v[86:89], v[142:145], v[182:185], v[86:89]
	v_mfma_f32_16x16x32_bf16 v[82:85], v[158:161], v[182:185], v[82:85]
	v_mfma_f32_16x16x32_bf16 v[70:73], v[138:141], v[202:205], v[70:73]
	v_mfma_f32_16x16x32_bf16 v[66:69], v[154:157], v[202:205], v[66:69]
	v_mfma_f32_16x16x32_bf16 v[70:73], v[142:145], v[206:209], v[70:73]
	v_mfma_f32_16x16x32_bf16 v[66:69], v[158:161], v[206:209], v[66:69]
	s_barrier
	s_setprio 0
	s_add_i32 s0, s54, s39
	v_lshl_add_u64 v[188:189], s[30:31], 0, v[186:187]
	s_mov_b32 m0, s0
	ds_read_b128 v[162:165], v238 offset:16384
	ds_read_b128 v[166:169], v238 offset:17408
	ds_read_b128 v[170:173], v238 offset:18432
	ds_read_b128 v[174:177], v238 offset:19456
	ds_read_b128 v[178:181], v238 offset:20480
	ds_read_b128 v[182:185], v238 offset:21504
	ds_read_b128 v[202:205], v238 offset:22528
	ds_read_b128 v[206:209], v238 offset:23552
	global_load_lds_dwordx4 v[188:189], off
	s_add_i32 m0, s0, 0x2000
	s_add_u32 s0, s30, 0x80000
	v_lshl_add_u64 v[210:211], s[30:31], 0, v[196:197]
	s_addc_u32 s1, s31, 0
	s_add_i32 s54, s55, s39
	global_load_lds_dwordx4 v[210:211], off
	v_lshl_add_u64 v[212:213], s[0:1], 0, v[186:187]
	s_mov_b32 m0, s54
	v_lshl_add_u64 v[214:215], s[34:35], 0, v[194:195]
	global_load_lds_dwordx4 v[212:213], off
	v_lshl_add_u64 v[212:213], s[0:1], 0, v[196:197]
	s_add_i32 m0, s54, 0x2000
	s_nop 0
	global_load_lds_dwordx4 v[212:213], off
	v_lshl_add_u64 v[212:213], s[34:35], 0, v[192:193]
	s_mov_b32 m0, s40
	s_nop 0
	global_load_lds_dwordx4 v[212:213], off
	s_mov_b32 m0, s41
	s_nop 0
	global_load_lds_dwordx4 v[214:215], off
	s_waitcnt vmcnt(8)
	s_waitcnt lgkmcnt(0)
	s_setprio 1
	s_barrier

	v_mfma_f32_16x16x32_bf16 v[62:65], v[90:93], v[162:165], v[62:65]
	v_mfma_f32_16x16x32_bf16 v[58:61], v[114:117], v[162:165], v[58:61]
	v_mfma_f32_16x16x32_bf16 v[62:65], v[102:105], v[166:169], v[62:65]
	v_mfma_f32_16x16x32_bf16 v[58:61], v[126:129], v[166:169], v[58:61]
	v_mfma_f32_16x16x32_bf16 v[46:49], v[90:93], v[170:173], v[46:49]
	v_mfma_f32_16x16x32_bf16 v[42:45], v[114:117], v[170:173], v[42:45]
	v_mfma_f32_16x16x32_bf16 v[46:49], v[102:105], v[174:177], v[46:49]
	v_mfma_f32_16x16x32_bf16 v[42:45], v[126:129], v[174:177], v[42:45]
	v_mfma_f32_16x16x32_bf16 v[30:33], v[90:93], v[178:181], v[30:33]
	v_mfma_f32_16x16x32_bf16 v[26:29], v[114:117], v[178:181], v[26:29]
	v_mfma_f32_16x16x32_bf16 v[30:33], v[102:105], v[182:185], v[30:33]
	v_mfma_f32_16x16x32_bf16 v[26:29], v[126:129], v[182:185], v[26:29]
	v_mfma_f32_16x16x32_bf16 v[14:17], v[90:93], v[202:205], v[14:17]
	v_mfma_f32_16x16x32_bf16 v[10:13], v[114:117], v[202:205], v[10:13]
	v_mfma_f32_16x16x32_bf16 v[14:17], v[102:105], v[206:209], v[14:17]
	v_mfma_f32_16x16x32_bf16 v[10:13], v[126:129], v[206:209], v[10:13]


	v_mfma_f32_16x16x32_bf16 v[54:57], v[138:141], v[162:165], v[54:57]
	v_mfma_f32_16x16x32_bf16 v[50:53], v[154:157], v[162:165], v[50:53]
	v_mfma_f32_16x16x32_bf16 v[54:57], v[142:145], v[166:169], v[54:57]
	v_mfma_f32_16x16x32_bf16 v[50:53], v[158:161], v[166:169], v[50:53]
	v_mfma_f32_16x16x32_bf16 v[38:41], v[138:141], v[170:173], v[38:41]
	v_mfma_f32_16x16x32_bf16 v[34:37], v[154:157], v[170:173], v[34:37]
	v_mfma_f32_16x16x32_bf16 v[38:41], v[142:145], v[174:177], v[38:41]
	v_mfma_f32_16x16x32_bf16 v[34:37], v[158:161], v[174:177], v[34:37]
	v_mfma_f32_16x16x32_bf16 v[22:25], v[138:141], v[178:181], v[22:25]
	v_mfma_f32_16x16x32_bf16 v[18:21], v[154:157], v[178:181], v[18:21]
	v_mfma_f32_16x16x32_bf16 v[22:25], v[142:145], v[182:185], v[22:25]
	v_mfma_f32_16x16x32_bf16 v[18:21], v[158:161], v[182:185], v[18:21]
	v_mfma_f32_16x16x32_bf16 v[6:9], v[138:141], v[202:205], v[6:9]
	v_mfma_f32_16x16x32_bf16 v[2:5], v[154:157], v[202:205], v[2:5]
	v_mfma_f32_16x16x32_bf16 v[6:9], v[142:145], v[206:209], v[6:9]
	v_mfma_f32_16x16x32_bf16 v[2:5], v[158:161], v[206:209], v[2:5]
	s_barrier
	s_setprio 0
	s_add_i32 s54, 0, 0x18000
	s_add_i32 s55, 0, 0x1c000
	v_add_u32_e32 v126, s54, v237
	v_add_u32_e32 v158, s55, v237
	ds_read_b128 v[90:93], v126
	ds_read_b128 v[102:105], v126 offset:1024
	ds_read_b128 v[114:117], v126 offset:2048
	ds_read_b128 v[126:129], v126 offset:3072
	ds_read_b128 v[138:141], v158
	ds_read_b128 v[142:145], v158 offset:1024
	ds_read_b128 v[154:157], v158 offset:2048
	ds_read_b128 v[158:161], v158 offset:3072
	s_add_u32 s0, s34, 0x80000
	s_addc_u32 s1, s35, 0
	s_mov_b32 m0, s42
	v_lshl_add_u64 v[216:217], s[0:1], 0, v[192:193]
	ds_read_b128 v[162:165], v238 offset:32768
	ds_read_b128 v[166:169], v238 offset:33792
	ds_read_b128 v[170:173], v238 offset:34816
	ds_read_b128 v[174:177], v238 offset:35840
	ds_read_b128 v[178:181], v238 offset:36864
	ds_read_b128 v[182:185], v238 offset:37888
	ds_read_b128 v[202:205], v238 offset:38912
	ds_read_b128 v[206:209], v238 offset:39936
	global_load_lds_dwordx4 v[216:217], off
	v_lshl_add_u64 v[216:217], s[0:1], 0, v[194:195]
	s_mov_b32 m0, s43
	s_nop 0
	global_load_lds_dwordx4 v[216:217], off
	s_waitcnt vmcnt(8)
	s_waitcnt lgkmcnt(0)
	s_setprio 1
	s_barrier

	v_mfma_f32_16x16x32_bf16 v[150:153], v[90:93], v[162:165], v[150:153]
	v_mfma_f32_16x16x32_bf16 v[146:149], v[114:117], v[162:165], v[146:149]
	v_mfma_f32_16x16x32_bf16 v[150:153], v[102:105], v[166:169], v[150:153]
	v_mfma_f32_16x16x32_bf16 v[146:149], v[126:129], v[166:169], v[146:149]
	v_mfma_f32_16x16x32_bf16 v[122:125], v[90:93], v[170:173], v[122:125]
	v_mfma_f32_16x16x32_bf16 v[118:121], v[114:117], v[170:173], v[118:121]
	v_mfma_f32_16x16x32_bf16 v[122:125], v[102:105], v[174:177], v[122:125]
	v_mfma_f32_16x16x32_bf16 v[118:121], v[126:129], v[174:177], v[118:121]
	v_mfma_f32_16x16x32_bf16 v[98:101], v[90:93], v[178:181], v[98:101]
	v_mfma_f32_16x16x32_bf16 v[94:97], v[114:117], v[178:181], v[94:97]
	v_mfma_f32_16x16x32_bf16 v[98:101], v[102:105], v[182:185], v[98:101]
	v_mfma_f32_16x16x32_bf16 v[94:97], v[126:129], v[182:185], v[94:97]
	v_mfma_f32_16x16x32_bf16 v[78:81], v[90:93], v[202:205], v[78:81]
	v_mfma_f32_16x16x32_bf16 v[74:77], v[114:117], v[202:205], v[74:77]
	v_mfma_f32_16x16x32_bf16 v[78:81], v[102:105], v[206:209], v[78:81]
	v_mfma_f32_16x16x32_bf16 v[74:77], v[126:129], v[206:209], v[74:77]


	v_mfma_f32_16x16x32_bf16 v[134:137], v[138:141], v[162:165], v[134:137]
	v_mfma_f32_16x16x32_bf16 v[130:133], v[154:157], v[162:165], v[130:133]
	v_mfma_f32_16x16x32_bf16 v[134:137], v[142:145], v[166:169], v[134:137]
	v_mfma_f32_16x16x32_bf16 v[130:133], v[158:161], v[166:169], v[130:133]
	v_mfma_f32_16x16x32_bf16 v[110:113], v[138:141], v[170:173], v[110:113]
	v_mfma_f32_16x16x32_bf16 v[106:109], v[154:157], v[170:173], v[106:109]
	v_mfma_f32_16x16x32_bf16 v[110:113], v[142:145], v[174:177], v[110:113]
	v_mfma_f32_16x16x32_bf16 v[106:109], v[158:161], v[174:177], v[106:109]
	v_mfma_f32_16x16x32_bf16 v[86:89], v[138:141], v[178:181], v[86:89]
	v_mfma_f32_16x16x32_bf16 v[82:85], v[154:157], v[178:181], v[82:85]
	v_mfma_f32_16x16x32_bf16 v[86:89], v[142:145], v[182:185], v[86:89]
	v_mfma_f32_16x16x32_bf16 v[82:85], v[158:161], v[182:185], v[82:85]
	v_mfma_f32_16x16x32_bf16 v[70:73], v[138:141], v[202:205], v[70:73]
	v_mfma_f32_16x16x32_bf16 v[66:69], v[154:157], v[202:205], v[66:69]
	v_mfma_f32_16x16x32_bf16 v[70:73], v[142:145], v[206:209], v[70:73]
	v_mfma_f32_16x16x32_bf16 v[66:69], v[158:161], v[206:209], v[66:69]
	s_barrier
	s_setprio 0
	s_add_i32 s0, s54, s39
	v_lshl_add_u64 v[188:189], v[188:189], 0, s[84:85]
	s_mov_b32 m0, s0
	ds_read_b128 v[162:165], v238 offset:49152
	ds_read_b128 v[166:169], v238 offset:50176
	ds_read_b128 v[170:173], v238 offset:51200
	ds_read_b128 v[174:177], v238 offset:52224
	ds_read_b128 v[178:181], v238 offset:53248
	ds_read_b128 v[182:185], v238 offset:54272
	ds_read_b128 v[202:205], v238 offset:55296
	ds_read_b128 v[206:209], v238 offset:56320
	global_load_lds_dwordx4 v[188:189], off
	s_add_i32 m0, s0, 0x2000
	s_add_u32 s0, s30, 0x80080
	v_lshl_add_u64 v[188:189], v[210:211], 0, s[84:85]
	s_addc_u32 s1, s31, 0
	s_add_i32 s30, s55, s39
	global_load_lds_dwordx4 v[188:189], off
	v_lshl_add_u64 v[188:189], s[0:1], 0, v[186:187]
	s_mov_b32 m0, s30
	s_nop 0
	global_load_lds_dwordx4 v[188:189], off
	v_lshl_add_u64 v[188:189], s[0:1], 0, v[196:197]
	s_add_i32 m0, s30, 0x2000
	s_nop 0
	global_load_lds_dwordx4 v[188:189], off
	v_lshl_add_u64 v[188:189], v[212:213], 0, s[84:85]
	s_mov_b32 m0, s47
	s_nop 0
	global_load_lds_dwordx4 v[188:189], off
	v_lshl_add_u64 v[188:189], v[214:215], 0, s[84:85]
	s_mov_b32 m0, s48
	s_nop 0
	global_load_lds_dwordx4 v[188:189], off
	s_waitcnt vmcnt(8)
	s_waitcnt lgkmcnt(0)
	s_setprio 1
	s_barrier

	v_mfma_f32_16x16x32_bf16 v[62:65], v[90:93], v[162:165], v[62:65]
	v_mfma_f32_16x16x32_bf16 v[58:61], v[114:117], v[162:165], v[58:61]
	v_mfma_f32_16x16x32_bf16 v[62:65], v[102:105], v[166:169], v[62:65]
	v_mfma_f32_16x16x32_bf16 v[58:61], v[126:129], v[166:169], v[58:61]
	v_mfma_f32_16x16x32_bf16 v[46:49], v[90:93], v[170:173], v[46:49]
	v_mfma_f32_16x16x32_bf16 v[42:45], v[114:117], v[170:173], v[42:45]
	v_mfma_f32_16x16x32_bf16 v[46:49], v[102:105], v[174:177], v[46:49]
	v_mfma_f32_16x16x32_bf16 v[42:45], v[126:129], v[174:177], v[42:45]
	v_mfma_f32_16x16x32_bf16 v[30:33], v[90:93], v[178:181], v[30:33]
	v_mfma_f32_16x16x32_bf16 v[26:29], v[114:117], v[178:181], v[26:29]
	v_mfma_f32_16x16x32_bf16 v[30:33], v[102:105], v[182:185], v[30:33]
	v_mfma_f32_16x16x32_bf16 v[26:29], v[126:129], v[182:185], v[26:29]
	v_mfma_f32_16x16x32_bf16 v[14:17], v[90:93], v[202:205], v[14:17]
	v_mfma_f32_16x16x32_bf16 v[10:13], v[114:117], v[202:205], v[10:13]
	v_mfma_f32_16x16x32_bf16 v[14:17], v[102:105], v[206:209], v[14:17]
	v_mfma_f32_16x16x32_bf16 v[10:13], v[126:129], v[206:209], v[10:13]


	v_mfma_f32_16x16x32_bf16 v[54:57], v[138:141], v[162:165], v[54:57]
	v_mfma_f32_16x16x32_bf16 v[50:53], v[154:157], v[162:165], v[50:53]
	v_mfma_f32_16x16x32_bf16 v[54:57], v[142:145], v[166:169], v[54:57]
	v_mfma_f32_16x16x32_bf16 v[50:53], v[158:161], v[166:169], v[50:53]
	v_mfma_f32_16x16x32_bf16 v[38:41], v[138:141], v[170:173], v[38:41]
	v_mfma_f32_16x16x32_bf16 v[34:37], v[154:157], v[170:173], v[34:37]
	v_mfma_f32_16x16x32_bf16 v[38:41], v[142:145], v[174:177], v[38:41]
	v_mfma_f32_16x16x32_bf16 v[34:37], v[158:161], v[174:177], v[34:37]
	v_mfma_f32_16x16x32_bf16 v[22:25], v[138:141], v[178:181], v[22:25]
	v_mfma_f32_16x16x32_bf16 v[18:21], v[154:157], v[178:181], v[18:21]
	v_mfma_f32_16x16x32_bf16 v[22:25], v[142:145], v[182:185], v[22:25]
	v_mfma_f32_16x16x32_bf16 v[18:21], v[158:161], v[182:185], v[18:21]
	v_mfma_f32_16x16x32_bf16 v[6:9], v[138:141], v[202:205], v[6:9]
	v_mfma_f32_16x16x32_bf16 v[2:5], v[154:157], v[202:205], v[2:5]
	v_mfma_f32_16x16x32_bf16 v[6:9], v[142:145], v[206:209], v[6:9]
	v_mfma_f32_16x16x32_bf16 v[2:5], v[158:161], v[206:209], v[2:5]
	s_barrier
	s_setprio 0
	s_add_i32 s53, s53, 2
	s_add_u32 s28, s28, 0x100
	s_addc_u32 s29, s29, 0
	s_add_u32 s51, s51, 0x100
	s_addc_u32 s52, s52, 0
	s_cmp_gt_u32 s53, 29
	s_cbranch_scc0 .LBB0_1126
	s_and_b64 vcc, exec, s[14:15]
	s_cbranch_vccz .LBB0_1129
	s_barrier
